# gate row-statistics pass: single trip with 28+4 loads in flight
# baseline (speedup 1.0000x reference)
; __device__ __forceinline__ float bf_lo(unsigned w) { return __uint_as_float(w << 16); }
; __device__ __forceinline__ float bf_hi(unsigned w) { return __uint_as_float(w & 0xffff0000u); }
; __device__ __forceinline__ float shx(float v, int o, int lane) { return __int_as_float(__builtin_amdgcn_ds_bpermute((lane ^ o) << 2, __float_as_int(v))); }
; __device__ __forceinline__ void gate_unit(LAS unsigned char* lds, bf16_t* Zg, int ch, const bf16_t* wsb, const float* ln_g, const float* ln_b, const float* b_s, bool dostore = true) {
;     ...
;         const int row = tid >> 2, part = tid & 3; const bf16_t* src = Zc + (size_t)row * ZLD + COL_VB + part * 8;
;         float s = 0.f, s2 = 0.f;
; #pragma unroll 8
;         for (int i = 0; i < 32; ++i) { const u32x4 w = *(const u32x4*)(src + i * 32);
; #pragma unroll
;             for (int e = 0; e < 4; ++e) { const float a = bf_lo(w[e]), b = bf_hi(w[e]); s += a + b; s2 += a * a + b * b; } }
;         s += shx(s, 1, lane); s += shx(s, 2, lane); s2 += shx(s2, 1, lane); s2 += shx(s2, 2, lane);
.LBB0_179:
	v_lshl_add_u64 v[14:15], v[2:3], 0, s[4:5]
	global_load_dwordx4 v[80:83], v[14:15], off offset:-256
	global_load_dwordx4 v[84:87], v[14:15], off offset:-192
	global_load_dwordx4 v[88:91], v[14:15], off offset:-128
	global_load_dwordx4 v[92:95], v[14:15], off offset:-64
	global_load_dwordx4 v[96:99], v[14:15], off
	global_load_dwordx4 v[100:103], v[14:15], off offset:64
	global_load_dwordx4 v[104:107], v[14:15], off offset:128
	global_load_dwordx4 v[108:111], v[14:15], off offset:192
	global_load_dwordx4 v[112:115], v[14:15], off offset:256
	global_load_dwordx4 v[116:119], v[14:15], off offset:320
	global_load_dwordx4 v[120:123], v[14:15], off offset:384
	global_load_dwordx4 v[124:127], v[14:15], off offset:448
	global_load_dwordx4 v[128:131], v[14:15], off offset:512
	global_load_dwordx4 v[132:135], v[14:15], off offset:576
	global_load_dwordx4 v[136:139], v[14:15], off offset:640
	global_load_dwordx4 v[140:143], v[14:15], off offset:704
	global_load_dwordx4 v[144:147], v[14:15], off offset:768
	global_load_dwordx4 v[148:151], v[14:15], off offset:832
	global_load_dwordx4 v[152:155], v[14:15], off offset:896
	global_load_dwordx4 v[156:159], v[14:15], off offset:960
	global_load_dwordx4 v[160:163], v[14:15], off offset:1024
	global_load_dwordx4 v[164:167], v[14:15], off offset:1088
	global_load_dwordx4 v[168:171], v[14:15], off offset:1152
	global_load_dwordx4 v[172:175], v[14:15], off offset:1216
	global_load_dwordx4 v[176:179], v[14:15], off offset:1280
	global_load_dwordx4 v[180:183], v[14:15], off offset:1344
	global_load_dwordx4 v[184:187], v[14:15], off offset:1408
	global_load_dwordx4 v[188:191], v[14:15], off offset:1472
	s_add_u32 s4, s4, 0x800
	s_addc_u32 s5, s5, 0
	s_cmpk_eq_i32 s4, 0x800
	s_waitcnt vmcnt(27)
	v_lshlrev_b32_e32 v17, 16, v81
	v_lshlrev_b32_e32 v16, 16, v80
	v_and_b32_e32 v81, 0xffff0000, v81
	v_and_b32_e32 v80, 0xffff0000, v80
	v_pk_add_f32 v[18:19], v[16:17], v[80:81]
	v_pk_mul_f32 v[80:81], v[80:81], v[80:81]
	v_pk_add_f32 v[20:21], v[4:5], v[18:19]
	v_pk_fma_f32 v[80:81], v[16:17], v[16:17], v[80:81]
	s_nop 0
	v_add_f32_e32 v0, v5, v80
	v_pk_add_f32 v[4:5], v[80:81], v[0:1] op_sel_hi:[1,0]
	v_and_b32_e32 v80, 0xffff0000, v82
	v_lshlrev_b32_e32 v82, 16, v82
	v_and_b32_e32 v4, 0xffff0000, v83
	v_lshlrev_b32_e32 v83, 16, v83
	v_mov_b32_e32 v16, v82
	v_mov_b32_e32 v17, v80
	v_mul_f32_e32 v0, v82, v82
	v_mov_b32_e32 v81, v83
	v_pk_fma_f32 v[16:17], v[16:17], v[16:17], v[0:1] op_sel_hi:[1,1,0]
	v_pk_add_f32 v[80:81], v[82:83], v[80:81]
	v_mov_b32_e32 v16, v83
	v_pk_mul_f32 v[82:83], v[82:83], v[82:83]
	v_mul_f32_e32 v9, v4, v4
	v_mov_b32_e32 v81, v83
	v_pk_add_f32 v[82:83], v[18:19], v[20:21] op_sel:[1,0] op_sel_hi:[0,1]
	v_mov_b32_e32 v83, v9
	v_pk_add_f32 v[4:5], v[16:17], v[4:5]
	v_pk_add_f32 v[80:81], v[80:81], v[82:83]
	s_nop 0
	v_pk_add_f32 v[4:5], v[80:81], v[4:5]
	s_waitcnt vmcnt(26)
	v_lshlrev_b32_e32 v17, 16, v85
	v_lshlrev_b32_e32 v16, 16, v84
	v_and_b32_e32 v85, 0xffff0000, v85
	v_and_b32_e32 v84, 0xffff0000, v84
	v_pk_add_f32 v[18:19], v[16:17], v[84:85]
	v_pk_mul_f32 v[84:85], v[84:85], v[84:85]
	v_pk_add_f32 v[20:21], v[4:5], v[18:19]
	v_pk_fma_f32 v[84:85], v[16:17], v[16:17], v[84:85]
	s_nop 0
	v_add_f32_e32 v0, v5, v84
	v_pk_add_f32 v[4:5], v[84:85], v[0:1] op_sel_hi:[1,0]
	v_and_b32_e32 v84, 0xffff0000, v86
	v_lshlrev_b32_e32 v86, 16, v86
	v_and_b32_e32 v4, 0xffff0000, v87
	v_lshlrev_b32_e32 v87, 16, v87
	v_mov_b32_e32 v16, v86
	v_mov_b32_e32 v17, v84
	v_mul_f32_e32 v0, v86, v86
	v_mov_b32_e32 v85, v87
	v_pk_fma_f32 v[16:17], v[16:17], v[16:17], v[0:1] op_sel_hi:[1,1,0]
	v_pk_add_f32 v[84:85], v[86:87], v[84:85]
	v_mov_b32_e32 v16, v87
	v_pk_mul_f32 v[86:87], v[86:87], v[86:87]
	v_mul_f32_e32 v9, v4, v4
	v_mov_b32_e32 v85, v87
	v_pk_add_f32 v[86:87], v[18:19], v[20:21] op_sel:[1,0] op_sel_hi:[0,1]
	v_mov_b32_e32 v87, v9
	v_pk_add_f32 v[4:5], v[16:17], v[4:5]
	v_pk_add_f32 v[84:85], v[84:85], v[86:87]
	s_nop 0
	v_pk_add_f32 v[4:5], v[84:85], v[4:5]
	s_waitcnt vmcnt(25)
	v_lshlrev_b32_e32 v17, 16, v89
	v_lshlrev_b32_e32 v16, 16, v88
	v_and_b32_e32 v89, 0xffff0000, v89
	v_and_b32_e32 v88, 0xffff0000, v88
	v_pk_add_f32 v[18:19], v[16:17], v[88:89]
	v_pk_mul_f32 v[88:89], v[88:89], v[88:89]
	v_pk_add_f32 v[20:21], v[4:5], v[18:19]
	v_pk_fma_f32 v[88:89], v[16:17], v[16:17], v[88:89]
	s_nop 0
	v_add_f32_e32 v0, v5, v88
	v_pk_add_f32 v[4:5], v[88:89], v[0:1] op_sel_hi:[1,0]
	v_and_b32_e32 v88, 0xffff0000, v90
	v_lshlrev_b32_e32 v90, 16, v90
	v_and_b32_e32 v4, 0xffff0000, v91
	v_lshlrev_b32_e32 v91, 16, v91
	v_mov_b32_e32 v16, v90
	v_mov_b32_e32 v17, v88
	v_mul_f32_e32 v0, v90, v90
	v_mov_b32_e32 v89, v91
	v_pk_fma_f32 v[16:17], v[16:17], v[16:17], v[0:1] op_sel_hi:[1,1,0]
	v_pk_add_f32 v[88:89], v[90:91], v[88:89]
	v_mov_b32_e32 v16, v91
	v_pk_mul_f32 v[90:91], v[90:91], v[90:91]
	v_mul_f32_e32 v9, v4, v4
	v_mov_b32_e32 v89, v91
	v_pk_add_f32 v[90:91], v[18:19], v[20:21] op_sel:[1,0] op_sel_hi:[0,1]
	v_mov_b32_e32 v91, v9
	v_pk_add_f32 v[4:5], v[16:17], v[4:5]
	v_pk_add_f32 v[88:89], v[88:89], v[90:91]
	s_nop 0
	v_pk_add_f32 v[4:5], v[88:89], v[4:5]
	s_waitcnt vmcnt(24)
; __device__ __forceinline__ float bf_lo(unsigned w) { return __uint_as_float(w << 16); }
; __device__ __forceinline__ float bf_hi(unsigned w) { return __uint_as_float(w & 0xffff0000u); }
; __device__ __forceinline__ float shx(float v, int o, int lane) { return __int_as_float(__builtin_amdgcn_ds_bpermute((lane ^ o) << 2, __float_as_int(v))); }
; __device__ __forceinline__ void gate_unit(LAS unsigned char* lds, bf16_t* Zg, int ch, const bf16_t* wsb, const float* ln_g, const float* ln_b, const float* b_s, bool dostore = true) {
;     ...
;         const int row = tid >> 2, part = tid & 3; const bf16_t* src = Zc + (size_t)row * ZLD + COL_VB + part * 8;
;         float s = 0.f, s2 = 0.f;
; #pragma unroll 8
;         for (int i = 0; i < 32; ++i) { const u32x4 w = *(const u32x4*)(src + i * 32);
; #pragma unroll
;             for (int e = 0; e < 4; ++e) { const float a = bf_lo(w[e]), b = bf_hi(w[e]); s += a + b; s2 += a * a + b * b; } }
;         s += shx(s, 1, lane); s += shx(s, 2, lane); s2 += shx(s2, 1, lane); s2 += shx(s2, 2, lane);
	v_lshlrev_b32_e32 v17, 16, v93
	v_lshlrev_b32_e32 v16, 16, v92
	v_and_b32_e32 v93, 0xffff0000, v93
	v_and_b32_e32 v92, 0xffff0000, v92
	v_pk_add_f32 v[18:19], v[16:17], v[92:93]
	v_pk_mul_f32 v[92:93], v[92:93], v[92:93]
	v_pk_add_f32 v[20:21], v[4:5], v[18:19]
	v_pk_fma_f32 v[92:93], v[16:17], v[16:17], v[92:93]
	s_nop 0
	v_add_f32_e32 v0, v5, v92
	v_pk_add_f32 v[4:5], v[92:93], v[0:1] op_sel_hi:[1,0]
	v_and_b32_e32 v92, 0xffff0000, v94
	v_lshlrev_b32_e32 v94, 16, v94
	v_and_b32_e32 v4, 0xffff0000, v95
	v_lshlrev_b32_e32 v95, 16, v95
	v_mov_b32_e32 v16, v94
	v_mov_b32_e32 v17, v92
	v_mul_f32_e32 v0, v94, v94
	v_mov_b32_e32 v93, v95
	v_pk_fma_f32 v[16:17], v[16:17], v[16:17], v[0:1] op_sel_hi:[1,1,0]
	v_pk_add_f32 v[92:93], v[94:95], v[92:93]
	v_mov_b32_e32 v16, v95
	v_pk_mul_f32 v[94:95], v[94:95], v[94:95]
	v_mul_f32_e32 v9, v4, v4
	v_mov_b32_e32 v93, v95
	v_pk_add_f32 v[94:95], v[18:19], v[20:21] op_sel:[1,0] op_sel_hi:[0,1]
	v_mov_b32_e32 v95, v9
	v_pk_add_f32 v[4:5], v[16:17], v[4:5]
	v_pk_add_f32 v[92:93], v[92:93], v[94:95]
	s_nop 0
	v_pk_add_f32 v[4:5], v[92:93], v[4:5]
	global_load_dwordx4 v[80:83], v[14:15], off offset:1536
	global_load_dwordx4 v[84:87], v[14:15], off offset:1600
	global_load_dwordx4 v[88:91], v[14:15], off offset:1664
	global_load_dwordx4 v[92:95], v[14:15], off offset:1728
	s_waitcnt vmcnt(27)
	v_lshlrev_b32_e32 v17, 16, v97
	v_lshlrev_b32_e32 v16, 16, v96
	v_and_b32_e32 v97, 0xffff0000, v97
	v_and_b32_e32 v96, 0xffff0000, v96
	v_pk_add_f32 v[18:19], v[16:17], v[96:97]
	v_pk_mul_f32 v[96:97], v[96:97], v[96:97]
	v_pk_add_f32 v[20:21], v[4:5], v[18:19]
	v_pk_fma_f32 v[96:97], v[16:17], v[16:17], v[96:97]
	s_nop 0
	v_add_f32_e32 v0, v5, v96
	v_pk_add_f32 v[4:5], v[96:97], v[0:1] op_sel_hi:[1,0]
	v_and_b32_e32 v96, 0xffff0000, v98
	v_lshlrev_b32_e32 v98, 16, v98
	v_and_b32_e32 v4, 0xffff0000, v99
	v_lshlrev_b32_e32 v99, 16, v99
	v_mov_b32_e32 v16, v98
	v_mov_b32_e32 v17, v96
	v_mul_f32_e32 v0, v98, v98
	v_mov_b32_e32 v97, v99
	v_pk_fma_f32 v[16:17], v[16:17], v[16:17], v[0:1] op_sel_hi:[1,1,0]
	v_pk_add_f32 v[96:97], v[98:99], v[96:97]
	v_mov_b32_e32 v16, v99
	v_pk_mul_f32 v[98:99], v[98:99], v[98:99]
	v_mul_f32_e32 v9, v4, v4
	v_mov_b32_e32 v97, v99
	v_pk_add_f32 v[98:99], v[18:19], v[20:21] op_sel:[1,0] op_sel_hi:[0,1]
	v_mov_b32_e32 v99, v9
	v_pk_add_f32 v[4:5], v[16:17], v[4:5]
	v_pk_add_f32 v[96:97], v[96:97], v[98:99]
	s_nop 0
	v_pk_add_f32 v[4:5], v[96:97], v[4:5]
	s_waitcnt vmcnt(26)
	v_lshlrev_b32_e32 v17, 16, v101
	v_lshlrev_b32_e32 v16, 16, v100
	v_and_b32_e32 v101, 0xffff0000, v101
	v_and_b32_e32 v100, 0xffff0000, v100
	v_pk_add_f32 v[18:19], v[16:17], v[100:101]
	v_pk_mul_f32 v[100:101], v[100:101], v[100:101]
	v_pk_add_f32 v[20:21], v[4:5], v[18:19]
	v_pk_fma_f32 v[100:101], v[16:17], v[16:17], v[100:101]
	s_nop 0
	v_add_f32_e32 v0, v5, v100
	v_pk_add_f32 v[4:5], v[100:101], v[0:1] op_sel_hi:[1,0]
	v_and_b32_e32 v100, 0xffff0000, v102
	v_lshlrev_b32_e32 v102, 16, v102
	v_and_b32_e32 v4, 0xffff0000, v103
	v_lshlrev_b32_e32 v103, 16, v103
	v_mov_b32_e32 v16, v102
	v_mov_b32_e32 v17, v100
	v_mul_f32_e32 v0, v102, v102
	v_mov_b32_e32 v101, v103
	v_pk_fma_f32 v[16:17], v[16:17], v[16:17], v[0:1] op_sel_hi:[1,1,0]
	v_pk_add_f32 v[100:101], v[102:103], v[100:101]
	v_mov_b32_e32 v16, v103
	v_pk_mul_f32 v[102:103], v[102:103], v[102:103]
	v_mul_f32_e32 v9, v4, v4
	v_mov_b32_e32 v101, v103
	v_pk_add_f32 v[102:103], v[18:19], v[20:21] op_sel:[1,0] op_sel_hi:[0,1]
	v_mov_b32_e32 v103, v9
	v_pk_add_f32 v[4:5], v[16:17], v[4:5]
	v_pk_add_f32 v[100:101], v[100:101], v[102:103]
	s_nop 0
	v_pk_add_f32 v[4:5], v[100:101], v[4:5]
	s_waitcnt vmcnt(25)
	v_lshlrev_b32_e32 v17, 16, v105
	v_lshlrev_b32_e32 v16, 16, v104
	v_and_b32_e32 v105, 0xffff0000, v105
	v_and_b32_e32 v104, 0xffff0000, v104
	v_pk_add_f32 v[18:19], v[16:17], v[104:105]
	v_pk_mul_f32 v[104:105], v[104:105], v[104:105]
	v_pk_add_f32 v[20:21], v[4:5], v[18:19]
	v_pk_fma_f32 v[104:105], v[16:17], v[16:17], v[104:105]
	s_nop 0
	v_add_f32_e32 v0, v5, v104
	v_pk_add_f32 v[4:5], v[104:105], v[0:1] op_sel_hi:[1,0]
	v_and_b32_e32 v104, 0xffff0000, v106
	v_lshlrev_b32_e32 v106, 16, v106
	v_and_b32_e32 v4, 0xffff0000, v107
	v_lshlrev_b32_e32 v107, 16, v107
	v_mov_b32_e32 v16, v106
	v_mov_b32_e32 v17, v104
	v_mul_f32_e32 v0, v106, v106
	v_mov_b32_e32 v105, v107
	v_pk_fma_f32 v[16:17], v[16:17], v[16:17], v[0:1] op_sel_hi:[1,1,0]
	v_pk_add_f32 v[104:105], v[106:107], v[104:105]
	v_mov_b32_e32 v16, v107
	v_pk_mul_f32 v[106:107], v[106:107], v[106:107]
	v_mul_f32_e32 v9, v4, v4
	v_mov_b32_e32 v105, v107
	v_pk_add_f32 v[106:107], v[18:19], v[20:21] op_sel:[1,0] op_sel_hi:[0,1]
	v_mov_b32_e32 v107, v9
	v_pk_add_f32 v[4:5], v[16:17], v[4:5]
	v_pk_add_f32 v[104:105], v[104:105], v[106:107]
	s_nop 0
	v_pk_add_f32 v[4:5], v[104:105], v[4:5]
	s_waitcnt vmcnt(24)
	v_lshlrev_b32_e32 v15, 16, v109
	v_lshlrev_b32_e32 v14, 16, v108
	v_and_b32_e32 v109, 0xffff0000, v109
	v_and_b32_e32 v108, 0xffff0000, v108
	v_pk_add_f32 v[16:17], v[14:15], v[108:109]
	v_pk_mul_f32 v[108:109], v[108:109], v[108:109]
	v_pk_add_f32 v[18:19], v[4:5], v[16:17]
	v_pk_fma_f32 v[108:109], v[14:15], v[14:15], v[108:109]
	s_nop 0
	v_add_f32_e32 v0, v5, v108
	v_pk_add_f32 v[4:5], v[108:109], v[0:1] op_sel_hi:[1,0]
	v_and_b32_e32 v108, 0xffff0000, v110
	v_lshlrev_b32_e32 v110, 16, v110
	v_and_b32_e32 v4, 0xffff0000, v111
	v_lshlrev_b32_e32 v111, 16, v111
	v_mov_b32_e32 v14, v110
	v_mov_b32_e32 v15, v108
	v_mul_f32_e32 v0, v110, v110
	v_mov_b32_e32 v109, v111
	v_pk_fma_f32 v[14:15], v[14:15], v[14:15], v[0:1] op_sel_hi:[1,1,0]
	v_pk_add_f32 v[108:109], v[110:111], v[108:109]
	v_mov_b32_e32 v14, v111
	v_pk_mul_f32 v[110:111], v[110:111], v[110:111]
	v_mul_f32_e32 v9, v4, v4
	v_mov_b32_e32 v109, v111
	v_pk_add_f32 v[110:111], v[16:17], v[18:19] op_sel:[1,0] op_sel_hi:[0,1]
	v_mov_b32_e32 v111, v9
	v_pk_add_f32 v[4:5], v[14:15], v[4:5]
	v_pk_add_f32 v[108:109], v[108:109], v[110:111]
	s_nop 0
	v_pk_add_f32 v[4:5], v[108:109], v[4:5]
	s_waitcnt vmcnt(23)
; __device__ __forceinline__ float bf_lo(unsigned w) { return __uint_as_float(w << 16); }
; __device__ __forceinline__ float bf_hi(unsigned w) { return __uint_as_float(w & 0xffff0000u); }
; __device__ __forceinline__ float shx(float v, int o, int lane) { return __int_as_float(__builtin_amdgcn_ds_bpermute((lane ^ o) << 2, __float_as_int(v))); }
; __device__ __forceinline__ void gate_unit(LAS unsigned char* lds, bf16_t* Zg, int ch, const bf16_t* wsb, const float* ln_g, const float* ln_b, const float* b_s, bool dostore = true) {
;     ...
;         const int row = tid >> 2, part = tid & 3; const bf16_t* src = Zc + (size_t)row * ZLD + COL_VB + part * 8;
;         float s = 0.f, s2 = 0.f;
; #pragma unroll 8
;         for (int i = 0; i < 32; ++i) { const u32x4 w = *(const u32x4*)(src + i * 32);
; #pragma unroll
;             for (int e = 0; e < 4; ++e) { const float a = bf_lo(w[e]), b = bf_hi(w[e]); s += a + b; s2 += a * a + b * b; } }
;         s += shx(s, 1, lane); s += shx(s, 2, lane); s2 += shx(s2, 1, lane); s2 += shx(s2, 2, lane);
	v_lshlrev_b32_e32 v17, 16, v113
	v_lshlrev_b32_e32 v16, 16, v112
	v_and_b32_e32 v113, 0xffff0000, v113
	v_and_b32_e32 v112, 0xffff0000, v112
	v_pk_add_f32 v[18:19], v[16:17], v[112:113]
	v_pk_mul_f32 v[112:113], v[112:113], v[112:113]
	v_pk_add_f32 v[20:21], v[4:5], v[18:19]
	v_pk_fma_f32 v[112:113], v[16:17], v[16:17], v[112:113]
	s_nop 0
	v_add_f32_e32 v0, v5, v112
	v_pk_add_f32 v[4:5], v[112:113], v[0:1] op_sel_hi:[1,0]
	v_and_b32_e32 v112, 0xffff0000, v114
	v_lshlrev_b32_e32 v114, 16, v114
	v_and_b32_e32 v4, 0xffff0000, v115
	v_lshlrev_b32_e32 v115, 16, v115
	v_mov_b32_e32 v16, v114
	v_mov_b32_e32 v17, v112
	v_mul_f32_e32 v0, v114, v114
	v_mov_b32_e32 v113, v115
	v_pk_fma_f32 v[16:17], v[16:17], v[16:17], v[0:1] op_sel_hi:[1,1,0]
	v_pk_add_f32 v[112:113], v[114:115], v[112:113]
	v_mov_b32_e32 v16, v115
	v_pk_mul_f32 v[114:115], v[114:115], v[114:115]
	v_mul_f32_e32 v9, v4, v4
	v_mov_b32_e32 v113, v115
	v_pk_add_f32 v[114:115], v[18:19], v[20:21] op_sel:[1,0] op_sel_hi:[0,1]
	v_mov_b32_e32 v115, v9
	v_pk_add_f32 v[4:5], v[16:17], v[4:5]
	v_pk_add_f32 v[112:113], v[112:113], v[114:115]
	s_nop 0
	v_pk_add_f32 v[4:5], v[112:113], v[4:5]
	s_waitcnt vmcnt(22)
	v_lshlrev_b32_e32 v17, 16, v117
	v_lshlrev_b32_e32 v16, 16, v116
	v_and_b32_e32 v117, 0xffff0000, v117
	v_and_b32_e32 v116, 0xffff0000, v116
	v_pk_add_f32 v[18:19], v[16:17], v[116:117]
	v_pk_mul_f32 v[116:117], v[116:117], v[116:117]
	v_pk_add_f32 v[20:21], v[4:5], v[18:19]
	v_pk_fma_f32 v[116:117], v[16:17], v[16:17], v[116:117]
	s_nop 0
	v_add_f32_e32 v0, v5, v116
	v_pk_add_f32 v[4:5], v[116:117], v[0:1] op_sel_hi:[1,0]
	v_and_b32_e32 v116, 0xffff0000, v118
	v_lshlrev_b32_e32 v118, 16, v118
	v_and_b32_e32 v4, 0xffff0000, v119
	v_lshlrev_b32_e32 v119, 16, v119
	v_mov_b32_e32 v16, v118
	v_mov_b32_e32 v17, v116
	v_mul_f32_e32 v0, v118, v118
	v_mov_b32_e32 v117, v119
	v_pk_fma_f32 v[16:17], v[16:17], v[16:17], v[0:1] op_sel_hi:[1,1,0]
	v_pk_add_f32 v[116:117], v[118:119], v[116:117]
	v_mov_b32_e32 v16, v119
	v_pk_mul_f32 v[118:119], v[118:119], v[118:119]
	v_mul_f32_e32 v9, v4, v4
	v_mov_b32_e32 v117, v119
	v_pk_add_f32 v[118:119], v[18:19], v[20:21] op_sel:[1,0] op_sel_hi:[0,1]
	v_mov_b32_e32 v119, v9
	v_pk_add_f32 v[4:5], v[16:17], v[4:5]
	v_pk_add_f32 v[116:117], v[116:117], v[118:119]
	s_nop 0
	v_pk_add_f32 v[4:5], v[116:117], v[4:5]
	s_waitcnt vmcnt(21)
	v_lshlrev_b32_e32 v17, 16, v121
	v_lshlrev_b32_e32 v16, 16, v120
	v_and_b32_e32 v121, 0xffff0000, v121
	v_and_b32_e32 v120, 0xffff0000, v120
	v_pk_add_f32 v[18:19], v[16:17], v[120:121]
	v_pk_mul_f32 v[120:121], v[120:121], v[120:121]
	v_pk_add_f32 v[20:21], v[4:5], v[18:19]
	v_pk_fma_f32 v[120:121], v[16:17], v[16:17], v[120:121]
	s_nop 0
	v_add_f32_e32 v0, v5, v120
	v_pk_add_f32 v[4:5], v[120:121], v[0:1] op_sel_hi:[1,0]
	v_and_b32_e32 v120, 0xffff0000, v122
	v_lshlrev_b32_e32 v122, 16, v122
	v_and_b32_e32 v4, 0xffff0000, v123
	v_lshlrev_b32_e32 v123, 16, v123
	v_mov_b32_e32 v16, v122
	v_mov_b32_e32 v17, v120
	v_mul_f32_e32 v0, v122, v122
	v_mov_b32_e32 v121, v123
	v_pk_fma_f32 v[16:17], v[16:17], v[16:17], v[0:1] op_sel_hi:[1,1,0]
	v_pk_add_f32 v[120:121], v[122:123], v[120:121]
	v_mov_b32_e32 v16, v123
	v_pk_mul_f32 v[122:123], v[122:123], v[122:123]
	v_mul_f32_e32 v9, v4, v4
	v_mov_b32_e32 v121, v123
	v_pk_add_f32 v[122:123], v[18:19], v[20:21] op_sel:[1,0] op_sel_hi:[0,1]
	v_mov_b32_e32 v123, v9
	v_pk_add_f32 v[4:5], v[16:17], v[4:5]
	v_pk_add_f32 v[120:121], v[120:121], v[122:123]
	s_nop 0
	v_pk_add_f32 v[4:5], v[120:121], v[4:5]
	s_waitcnt vmcnt(20)
	v_lshlrev_b32_e32 v17, 16, v125
	v_lshlrev_b32_e32 v16, 16, v124
	v_and_b32_e32 v125, 0xffff0000, v125
	v_and_b32_e32 v124, 0xffff0000, v124
	v_pk_add_f32 v[18:19], v[16:17], v[124:125]
	v_pk_mul_f32 v[124:125], v[124:125], v[124:125]
	v_pk_add_f32 v[20:21], v[4:5], v[18:19]
	v_pk_fma_f32 v[124:125], v[16:17], v[16:17], v[124:125]
	s_nop 0
	v_add_f32_e32 v0, v5, v124
	v_pk_add_f32 v[4:5], v[124:125], v[0:1] op_sel_hi:[1,0]
	v_and_b32_e32 v124, 0xffff0000, v126
	v_lshlrev_b32_e32 v126, 16, v126
	v_and_b32_e32 v4, 0xffff0000, v127
	v_lshlrev_b32_e32 v127, 16, v127
	v_mov_b32_e32 v16, v126
	v_mov_b32_e32 v17, v124
	v_mul_f32_e32 v0, v126, v126
	v_mov_b32_e32 v125, v127
	v_pk_fma_f32 v[16:17], v[16:17], v[16:17], v[0:1] op_sel_hi:[1,1,0]
	v_pk_add_f32 v[124:125], v[126:127], v[124:125]
	v_mov_b32_e32 v16, v127
	v_pk_mul_f32 v[126:127], v[126:127], v[126:127]
	v_mul_f32_e32 v9, v4, v4
	v_mov_b32_e32 v125, v127
	v_pk_add_f32 v[126:127], v[18:19], v[20:21] op_sel:[1,0] op_sel_hi:[0,1]
	v_mov_b32_e32 v127, v9
	v_pk_add_f32 v[4:5], v[16:17], v[4:5]
	v_pk_add_f32 v[124:125], v[124:125], v[126:127]
	s_nop 0
	v_pk_add_f32 v[4:5], v[124:125], v[4:5]
	s_waitcnt vmcnt(19)
	v_lshlrev_b32_e32 v17, 16, v129
	v_lshlrev_b32_e32 v16, 16, v128
	v_and_b32_e32 v129, 0xffff0000, v129
	v_and_b32_e32 v128, 0xffff0000, v128
	v_pk_add_f32 v[18:19], v[16:17], v[128:129]
	v_pk_mul_f32 v[128:129], v[128:129], v[128:129]
	v_pk_add_f32 v[20:21], v[4:5], v[18:19]
	v_pk_fma_f32 v[128:129], v[16:17], v[16:17], v[128:129]
	s_nop 0
	v_add_f32_e32 v0, v5, v128
	v_pk_add_f32 v[4:5], v[128:129], v[0:1] op_sel_hi:[1,0]
	v_and_b32_e32 v128, 0xffff0000, v130
	v_lshlrev_b32_e32 v130, 16, v130
	v_and_b32_e32 v4, 0xffff0000, v131
	v_lshlrev_b32_e32 v131, 16, v131
	v_mov_b32_e32 v16, v130
	v_mov_b32_e32 v17, v128
	v_mul_f32_e32 v0, v130, v130
	v_mov_b32_e32 v129, v131
	v_pk_fma_f32 v[16:17], v[16:17], v[16:17], v[0:1] op_sel_hi:[1,1,0]
	v_pk_add_f32 v[128:129], v[130:131], v[128:129]
	v_mov_b32_e32 v16, v131
	v_pk_mul_f32 v[130:131], v[130:131], v[130:131]
	v_mul_f32_e32 v9, v4, v4
	v_mov_b32_e32 v129, v131
	v_pk_add_f32 v[130:131], v[18:19], v[20:21] op_sel:[1,0] op_sel_hi:[0,1]
	v_mov_b32_e32 v131, v9
	v_pk_add_f32 v[4:5], v[16:17], v[4:5]
	v_pk_add_f32 v[128:129], v[128:129], v[130:131]
	s_nop 0
	v_pk_add_f32 v[4:5], v[128:129], v[4:5]
	s_waitcnt vmcnt(18)
; __device__ __forceinline__ float bf_lo(unsigned w) { return __uint_as_float(w << 16); }
; __device__ __forceinline__ float bf_hi(unsigned w) { return __uint_as_float(w & 0xffff0000u); }
; __device__ __forceinline__ void gate_unit(LAS unsigned char* lds, bf16_t* Zg, int ch, const bf16_t* wsb, const float* ln_g, const float* ln_b, const float* b_s, bool dostore = true) {
;     ...
;         for (int i = 0; i < 32; ++i) { const u32x4 w = *(const u32x4*)(src + i * 32);
; #pragma unroll
;             for (int e = 0; e < 4; ++e) { const float a = bf_lo(w[e]), b = bf_hi(w[e]); s += a + b; s2 += a * a + b * b; } }
	v_lshlrev_b32_e32 v17, 16, v133
	v_lshlrev_b32_e32 v16, 16, v132
	v_and_b32_e32 v133, 0xffff0000, v133
	v_and_b32_e32 v132, 0xffff0000, v132
	v_pk_add_f32 v[18:19], v[16:17], v[132:133]
	v_pk_mul_f32 v[132:133], v[132:133], v[132:133]
	v_pk_add_f32 v[20:21], v[4:5], v[18:19]
	v_pk_fma_f32 v[132:133], v[16:17], v[16:17], v[132:133]
	s_nop 0
	v_add_f32_e32 v0, v5, v132
	v_pk_add_f32 v[4:5], v[132:133], v[0:1] op_sel_hi:[1,0]
	v_and_b32_e32 v132, 0xffff0000, v134
	v_lshlrev_b32_e32 v134, 16, v134
	v_and_b32_e32 v4, 0xffff0000, v135
	v_lshlrev_b32_e32 v135, 16, v135
	v_mov_b32_e32 v16, v134
	v_mov_b32_e32 v17, v132
	v_mul_f32_e32 v0, v134, v134
	v_mov_b32_e32 v133, v135
	v_pk_fma_f32 v[16:17], v[16:17], v[16:17], v[0:1] op_sel_hi:[1,1,0]
	v_pk_add_f32 v[132:133], v[134:135], v[132:133]
	v_mov_b32_e32 v16, v135
	v_pk_mul_f32 v[134:135], v[134:135], v[134:135]
	v_mul_f32_e32 v9, v4, v4
	v_mov_b32_e32 v133, v135
	v_pk_add_f32 v[134:135], v[18:19], v[20:21] op_sel:[1,0] op_sel_hi:[0,1]
	v_mov_b32_e32 v135, v9
	v_pk_add_f32 v[4:5], v[16:17], v[4:5]
	v_pk_add_f32 v[132:133], v[132:133], v[134:135]
	s_nop 0
	v_pk_add_f32 v[4:5], v[132:133], v[4:5]
	s_waitcnt vmcnt(17)
	v_lshlrev_b32_e32 v17, 16, v137
	v_lshlrev_b32_e32 v16, 16, v136
	v_and_b32_e32 v137, 0xffff0000, v137
	v_and_b32_e32 v136, 0xffff0000, v136
	v_pk_add_f32 v[18:19], v[16:17], v[136:137]
	v_pk_mul_f32 v[136:137], v[136:137], v[136:137]
	v_pk_add_f32 v[20:21], v[4:5], v[18:19]
	v_pk_fma_f32 v[136:137], v[16:17], v[16:17], v[136:137]
	s_nop 0
	v_add_f32_e32 v0, v5, v136
	v_pk_add_f32 v[4:5], v[136:137], v[0:1] op_sel_hi:[1,0]
	v_and_b32_e32 v136, 0xffff0000, v138
	v_lshlrev_b32_e32 v138, 16, v138
	v_and_b32_e32 v4, 0xffff0000, v139
	v_lshlrev_b32_e32 v139, 16, v139
	v_mov_b32_e32 v16, v138
	v_mov_b32_e32 v17, v136
	v_mul_f32_e32 v0, v138, v138
	v_mov_b32_e32 v137, v139
	v_pk_fma_f32 v[16:17], v[16:17], v[16:17], v[0:1] op_sel_hi:[1,1,0]
	v_pk_add_f32 v[136:137], v[138:139], v[136:137]
	v_mov_b32_e32 v16, v139
	v_pk_mul_f32 v[138:139], v[138:139], v[138:139]
	v_mul_f32_e32 v9, v4, v4
	v_mov_b32_e32 v137, v139
	v_pk_add_f32 v[138:139], v[18:19], v[20:21] op_sel:[1,0] op_sel_hi:[0,1]
	v_mov_b32_e32 v139, v9
	v_pk_add_f32 v[4:5], v[16:17], v[4:5]
	v_pk_add_f32 v[136:137], v[136:137], v[138:139]
	s_nop 0
	v_pk_add_f32 v[4:5], v[136:137], v[4:5]
	s_waitcnt vmcnt(16)
	v_lshlrev_b32_e32 v15, 16, v141
	v_lshlrev_b32_e32 v14, 16, v140
	v_and_b32_e32 v141, 0xffff0000, v141
	v_and_b32_e32 v140, 0xffff0000, v140
	v_pk_add_f32 v[16:17], v[14:15], v[140:141]
	v_pk_mul_f32 v[140:141], v[140:141], v[140:141]
	v_pk_add_f32 v[18:19], v[4:5], v[16:17]
	v_pk_fma_f32 v[140:141], v[14:15], v[14:15], v[140:141]
	s_nop 0
	v_add_f32_e32 v0, v5, v140
	v_pk_add_f32 v[4:5], v[140:141], v[0:1] op_sel_hi:[1,0]
	v_and_b32_e32 v140, 0xffff0000, v142
	v_lshlrev_b32_e32 v142, 16, v142
	v_and_b32_e32 v4, 0xffff0000, v143
	v_lshlrev_b32_e32 v143, 16, v143
	v_mov_b32_e32 v14, v142
	v_mov_b32_e32 v15, v140
	v_mul_f32_e32 v0, v142, v142
	v_mov_b32_e32 v141, v143
	v_pk_fma_f32 v[14:15], v[14:15], v[14:15], v[0:1] op_sel_hi:[1,1,0]
	v_pk_add_f32 v[140:141], v[142:143], v[140:141]
	v_mov_b32_e32 v14, v143
	v_pk_mul_f32 v[142:143], v[142:143], v[142:143]
	v_mul_f32_e32 v9, v4, v4
	v_mov_b32_e32 v141, v143
	v_pk_add_f32 v[142:143], v[16:17], v[18:19] op_sel:[1,0] op_sel_hi:[0,1]
	v_mov_b32_e32 v143, v9
	v_pk_add_f32 v[4:5], v[14:15], v[4:5]
	v_pk_add_f32 v[140:141], v[140:141], v[142:143]
	s_nop 0
	v_pk_add_f32 v[4:5], v[140:141], v[4:5]
	s_waitcnt vmcnt(15)
	v_lshlrev_b32_e32 v17, 16, v145
	v_lshlrev_b32_e32 v16, 16, v144
	v_and_b32_e32 v145, 0xffff0000, v145
	v_and_b32_e32 v144, 0xffff0000, v144
	v_pk_add_f32 v[18:19], v[16:17], v[144:145]
	v_pk_mul_f32 v[144:145], v[144:145], v[144:145]
	v_pk_add_f32 v[20:21], v[4:5], v[18:19]
	v_pk_fma_f32 v[144:145], v[16:17], v[16:17], v[144:145]
	s_nop 0
	v_add_f32_e32 v0, v5, v144
	v_pk_add_f32 v[4:5], v[144:145], v[0:1] op_sel_hi:[1,0]
	v_and_b32_e32 v144, 0xffff0000, v146
	v_lshlrev_b32_e32 v146, 16, v146
	v_and_b32_e32 v4, 0xffff0000, v147
	v_lshlrev_b32_e32 v147, 16, v147
	v_mov_b32_e32 v16, v146
	v_mov_b32_e32 v17, v144
	v_mul_f32_e32 v0, v146, v146
	v_mov_b32_e32 v145, v147
	v_pk_fma_f32 v[16:17], v[16:17], v[16:17], v[0:1] op_sel_hi:[1,1,0]
	v_pk_add_f32 v[144:145], v[146:147], v[144:145]
	v_mov_b32_e32 v16, v147
	v_pk_mul_f32 v[146:147], v[146:147], v[146:147]
	v_mul_f32_e32 v9, v4, v4
	v_mov_b32_e32 v145, v147
	v_pk_add_f32 v[146:147], v[18:19], v[20:21] op_sel:[1,0] op_sel_hi:[0,1]
	v_mov_b32_e32 v147, v9
	v_pk_add_f32 v[4:5], v[16:17], v[4:5]
	v_pk_add_f32 v[144:145], v[144:145], v[146:147]
	s_nop 0
	v_pk_add_f32 v[4:5], v[144:145], v[4:5]
	s_waitcnt vmcnt(14)
	v_lshlrev_b32_e32 v17, 16, v149
	v_lshlrev_b32_e32 v16, 16, v148
	v_and_b32_e32 v149, 0xffff0000, v149
	v_and_b32_e32 v148, 0xffff0000, v148
	v_pk_add_f32 v[18:19], v[16:17], v[148:149]
	v_pk_mul_f32 v[148:149], v[148:149], v[148:149]
	v_pk_add_f32 v[20:21], v[4:5], v[18:19]
	v_pk_fma_f32 v[148:149], v[16:17], v[16:17], v[148:149]
	s_nop 0
	v_add_f32_e32 v0, v5, v148
	v_pk_add_f32 v[4:5], v[148:149], v[0:1] op_sel_hi:[1,0]
	v_and_b32_e32 v148, 0xffff0000, v150
	v_lshlrev_b32_e32 v150, 16, v150
	v_and_b32_e32 v4, 0xffff0000, v151
	v_lshlrev_b32_e32 v151, 16, v151
	v_mov_b32_e32 v16, v150
	v_mov_b32_e32 v17, v148
	v_mul_f32_e32 v0, v150, v150
	v_mov_b32_e32 v149, v151
	v_pk_fma_f32 v[16:17], v[16:17], v[16:17], v[0:1] op_sel_hi:[1,1,0]
	v_pk_add_f32 v[148:149], v[150:151], v[148:149]
	v_mov_b32_e32 v16, v151
	v_pk_mul_f32 v[150:151], v[150:151], v[150:151]
	v_mul_f32_e32 v9, v4, v4
	v_mov_b32_e32 v149, v151
	v_pk_add_f32 v[150:151], v[18:19], v[20:21] op_sel:[1,0] op_sel_hi:[0,1]
	v_mov_b32_e32 v151, v9
	v_pk_add_f32 v[4:5], v[16:17], v[4:5]
	v_pk_add_f32 v[148:149], v[148:149], v[150:151]
	s_nop 0
	v_pk_add_f32 v[4:5], v[148:149], v[4:5]
	s_waitcnt vmcnt(13)
; __device__ __forceinline__ float bf_lo(unsigned w) { return __uint_as_float(w << 16); }
; __device__ __forceinline__ float bf_hi(unsigned w) { return __uint_as_float(w & 0xffff0000u); }
; __device__ __forceinline__ void gate_unit(LAS unsigned char* lds, bf16_t* Zg, int ch, const bf16_t* wsb, const float* ln_g, const float* ln_b, const float* b_s, bool dostore = true) {
;     ...
;         for (int i = 0; i < 32; ++i) { const u32x4 w = *(const u32x4*)(src + i * 32);
; #pragma unroll
;             for (int e = 0; e < 4; ++e) { const float a = bf_lo(w[e]), b = bf_hi(w[e]); s += a + b; s2 += a * a + b * b; } }
	v_lshlrev_b32_e32 v17, 16, v153
	v_lshlrev_b32_e32 v16, 16, v152
	v_and_b32_e32 v153, 0xffff0000, v153
	v_and_b32_e32 v152, 0xffff0000, v152
	v_pk_add_f32 v[18:19], v[16:17], v[152:153]
	v_pk_mul_f32 v[152:153], v[152:153], v[152:153]
	v_pk_add_f32 v[20:21], v[4:5], v[18:19]
	v_pk_fma_f32 v[152:153], v[16:17], v[16:17], v[152:153]
	s_nop 0
	v_add_f32_e32 v0, v5, v152
	v_pk_add_f32 v[4:5], v[152:153], v[0:1] op_sel_hi:[1,0]
	v_and_b32_e32 v152, 0xffff0000, v154
	v_lshlrev_b32_e32 v154, 16, v154
	v_and_b32_e32 v4, 0xffff0000, v155
	v_lshlrev_b32_e32 v155, 16, v155
	v_mov_b32_e32 v16, v154
	v_mov_b32_e32 v17, v152
	v_mul_f32_e32 v0, v154, v154
	v_mov_b32_e32 v153, v155
	v_pk_fma_f32 v[16:17], v[16:17], v[16:17], v[0:1] op_sel_hi:[1,1,0]
	v_pk_add_f32 v[152:153], v[154:155], v[152:153]
	v_mov_b32_e32 v16, v155
	v_pk_mul_f32 v[154:155], v[154:155], v[154:155]
	v_mul_f32_e32 v9, v4, v4
	v_mov_b32_e32 v153, v155
	v_pk_add_f32 v[154:155], v[18:19], v[20:21] op_sel:[1,0] op_sel_hi:[0,1]
	v_mov_b32_e32 v155, v9
	v_pk_add_f32 v[4:5], v[16:17], v[4:5]
	v_pk_add_f32 v[152:153], v[152:153], v[154:155]
	s_nop 0
	v_pk_add_f32 v[4:5], v[152:153], v[4:5]
	s_waitcnt vmcnt(12)
	v_lshlrev_b32_e32 v17, 16, v157
	v_lshlrev_b32_e32 v16, 16, v156
	v_and_b32_e32 v157, 0xffff0000, v157
	v_and_b32_e32 v156, 0xffff0000, v156
	v_pk_add_f32 v[18:19], v[16:17], v[156:157]
	v_pk_mul_f32 v[156:157], v[156:157], v[156:157]
	v_pk_add_f32 v[20:21], v[4:5], v[18:19]
	v_pk_fma_f32 v[156:157], v[16:17], v[16:17], v[156:157]
	s_nop 0
	v_add_f32_e32 v0, v5, v156
	v_pk_add_f32 v[4:5], v[156:157], v[0:1] op_sel_hi:[1,0]
	v_and_b32_e32 v156, 0xffff0000, v158
	v_lshlrev_b32_e32 v158, 16, v158
	v_and_b32_e32 v4, 0xffff0000, v159
	v_lshlrev_b32_e32 v159, 16, v159
	v_mov_b32_e32 v16, v158
	v_mov_b32_e32 v17, v156
	v_mul_f32_e32 v0, v158, v158
	v_mov_b32_e32 v157, v159
	v_pk_fma_f32 v[16:17], v[16:17], v[16:17], v[0:1] op_sel_hi:[1,1,0]
	v_pk_add_f32 v[156:157], v[158:159], v[156:157]
	v_mov_b32_e32 v16, v159
	v_pk_mul_f32 v[158:159], v[158:159], v[158:159]
	v_mul_f32_e32 v9, v4, v4
	v_mov_b32_e32 v157, v159
	v_pk_add_f32 v[158:159], v[18:19], v[20:21] op_sel:[1,0] op_sel_hi:[0,1]
	v_mov_b32_e32 v159, v9
	v_pk_add_f32 v[4:5], v[16:17], v[4:5]
	v_pk_add_f32 v[156:157], v[156:157], v[158:159]
	s_nop 0
	v_pk_add_f32 v[4:5], v[156:157], v[4:5]
	s_waitcnt vmcnt(11)
	v_lshlrev_b32_e32 v17, 16, v161
	v_lshlrev_b32_e32 v16, 16, v160
	v_and_b32_e32 v161, 0xffff0000, v161
	v_and_b32_e32 v160, 0xffff0000, v160
	v_pk_add_f32 v[18:19], v[16:17], v[160:161]
	v_pk_mul_f32 v[160:161], v[160:161], v[160:161]
	v_pk_add_f32 v[20:21], v[4:5], v[18:19]
	v_pk_fma_f32 v[160:161], v[16:17], v[16:17], v[160:161]
	s_nop 0
	v_add_f32_e32 v0, v5, v160
	v_pk_add_f32 v[4:5], v[160:161], v[0:1] op_sel_hi:[1,0]
	v_and_b32_e32 v160, 0xffff0000, v162
	v_lshlrev_b32_e32 v162, 16, v162
	v_and_b32_e32 v4, 0xffff0000, v163
	v_lshlrev_b32_e32 v163, 16, v163
	v_mov_b32_e32 v16, v162
	v_mov_b32_e32 v17, v160
	v_mul_f32_e32 v0, v162, v162
	v_mov_b32_e32 v161, v163
	v_pk_fma_f32 v[16:17], v[16:17], v[16:17], v[0:1] op_sel_hi:[1,1,0]
	v_pk_add_f32 v[160:161], v[162:163], v[160:161]
	v_mov_b32_e32 v16, v163
	v_pk_mul_f32 v[162:163], v[162:163], v[162:163]
	v_mul_f32_e32 v9, v4, v4
	v_mov_b32_e32 v161, v163
	v_pk_add_f32 v[162:163], v[18:19], v[20:21] op_sel:[1,0] op_sel_hi:[0,1]
	v_mov_b32_e32 v163, v9
	v_pk_add_f32 v[4:5], v[16:17], v[4:5]
	v_pk_add_f32 v[160:161], v[160:161], v[162:163]
	s_nop 0
	v_pk_add_f32 v[4:5], v[160:161], v[4:5]
	s_waitcnt vmcnt(10)
	v_lshlrev_b32_e32 v17, 16, v165
	v_lshlrev_b32_e32 v16, 16, v164
	v_and_b32_e32 v165, 0xffff0000, v165
	v_and_b32_e32 v164, 0xffff0000, v164
	v_pk_add_f32 v[18:19], v[16:17], v[164:165]
	v_pk_mul_f32 v[164:165], v[164:165], v[164:165]
	v_pk_add_f32 v[20:21], v[4:5], v[18:19]
	v_pk_fma_f32 v[164:165], v[16:17], v[16:17], v[164:165]
	s_nop 0
	v_add_f32_e32 v0, v5, v164
	v_pk_add_f32 v[4:5], v[164:165], v[0:1] op_sel_hi:[1,0]
	v_and_b32_e32 v164, 0xffff0000, v166
	v_lshlrev_b32_e32 v166, 16, v166
	v_and_b32_e32 v4, 0xffff0000, v167
	v_lshlrev_b32_e32 v167, 16, v167
	v_mov_b32_e32 v16, v166
	v_mov_b32_e32 v17, v164
	v_mul_f32_e32 v0, v166, v166
	v_mov_b32_e32 v165, v167
	v_pk_fma_f32 v[16:17], v[16:17], v[16:17], v[0:1] op_sel_hi:[1,1,0]
	v_pk_add_f32 v[164:165], v[166:167], v[164:165]
	v_mov_b32_e32 v16, v167
	v_pk_mul_f32 v[166:167], v[166:167], v[166:167]
	v_mul_f32_e32 v9, v4, v4
	v_mov_b32_e32 v165, v167
	v_pk_add_f32 v[166:167], v[18:19], v[20:21] op_sel:[1,0] op_sel_hi:[0,1]
	v_mov_b32_e32 v167, v9
	v_pk_add_f32 v[4:5], v[16:17], v[4:5]
	v_pk_add_f32 v[164:165], v[164:165], v[166:167]
	s_nop 0
	v_pk_add_f32 v[4:5], v[164:165], v[4:5]
	s_waitcnt vmcnt(9)
	v_lshlrev_b32_e32 v17, 16, v169
	v_lshlrev_b32_e32 v16, 16, v168
	v_and_b32_e32 v169, 0xffff0000, v169
	v_and_b32_e32 v168, 0xffff0000, v168
	v_pk_add_f32 v[18:19], v[16:17], v[168:169]
	v_pk_mul_f32 v[168:169], v[168:169], v[168:169]
	v_pk_add_f32 v[20:21], v[4:5], v[18:19]
	v_pk_fma_f32 v[168:169], v[16:17], v[16:17], v[168:169]
	s_nop 0
	v_add_f32_e32 v0, v5, v168
	v_pk_add_f32 v[4:5], v[168:169], v[0:1] op_sel_hi:[1,0]
	v_and_b32_e32 v168, 0xffff0000, v170
	v_lshlrev_b32_e32 v170, 16, v170
	v_and_b32_e32 v4, 0xffff0000, v171
	v_lshlrev_b32_e32 v171, 16, v171
	v_mov_b32_e32 v16, v170
	v_mov_b32_e32 v17, v168
	v_mul_f32_e32 v0, v170, v170
	v_mov_b32_e32 v169, v171
	v_pk_fma_f32 v[16:17], v[16:17], v[16:17], v[0:1] op_sel_hi:[1,1,0]
	v_pk_add_f32 v[168:169], v[170:171], v[168:169]
	v_mov_b32_e32 v16, v171
	v_pk_mul_f32 v[170:171], v[170:171], v[170:171]
	v_mul_f32_e32 v9, v4, v4
	v_mov_b32_e32 v169, v171
	v_pk_add_f32 v[170:171], v[18:19], v[20:21] op_sel:[1,0] op_sel_hi:[0,1]
	v_mov_b32_e32 v171, v9
	v_pk_add_f32 v[4:5], v[16:17], v[4:5]
	v_pk_add_f32 v[168:169], v[168:169], v[170:171]
	s_nop 0
	v_pk_add_f32 v[4:5], v[168:169], v[4:5]
	s_waitcnt vmcnt(8)
; __device__ __forceinline__ float bf_lo(unsigned w) { return __uint_as_float(w << 16); }
; __device__ __forceinline__ float bf_hi(unsigned w) { return __uint_as_float(w & 0xffff0000u); }
; __device__ __forceinline__ void gate_unit(LAS unsigned char* lds, bf16_t* Zg, int ch, const bf16_t* wsb, const float* ln_g, const float* ln_b, const float* b_s, bool dostore = true) {
;     ...
;         for (int i = 0; i < 32; ++i) { const u32x4 w = *(const u32x4*)(src + i * 32);
; #pragma unroll
;             for (int e = 0; e < 4; ++e) { const float a = bf_lo(w[e]), b = bf_hi(w[e]); s += a + b; s2 += a * a + b * b; } }
	v_lshlrev_b32_e32 v15, 16, v173
	v_lshlrev_b32_e32 v14, 16, v172
	v_and_b32_e32 v173, 0xffff0000, v173
	v_and_b32_e32 v172, 0xffff0000, v172
	v_pk_add_f32 v[16:17], v[14:15], v[172:173]
	v_pk_mul_f32 v[172:173], v[172:173], v[172:173]
	v_pk_add_f32 v[18:19], v[4:5], v[16:17]
	v_pk_fma_f32 v[172:173], v[14:15], v[14:15], v[172:173]
	s_nop 0
	v_add_f32_e32 v0, v5, v172
	v_pk_add_f32 v[4:5], v[172:173], v[0:1] op_sel_hi:[1,0]
	v_and_b32_e32 v172, 0xffff0000, v174
	v_lshlrev_b32_e32 v174, 16, v174
	v_and_b32_e32 v4, 0xffff0000, v175
	v_lshlrev_b32_e32 v175, 16, v175
	v_mov_b32_e32 v14, v174
	v_mov_b32_e32 v15, v172
	v_mul_f32_e32 v0, v174, v174
	v_mov_b32_e32 v173, v175
	v_pk_fma_f32 v[14:15], v[14:15], v[14:15], v[0:1] op_sel_hi:[1,1,0]
	v_pk_add_f32 v[172:173], v[174:175], v[172:173]
	v_mov_b32_e32 v14, v175
	v_pk_mul_f32 v[174:175], v[174:175], v[174:175]
	v_mul_f32_e32 v9, v4, v4
	v_mov_b32_e32 v173, v175
	v_pk_add_f32 v[174:175], v[16:17], v[18:19] op_sel:[1,0] op_sel_hi:[0,1]
	v_mov_b32_e32 v175, v9
	v_pk_add_f32 v[4:5], v[14:15], v[4:5]
	v_pk_add_f32 v[172:173], v[172:173], v[174:175]
	s_nop 0
	v_pk_add_f32 v[4:5], v[172:173], v[4:5]
	s_waitcnt vmcnt(7)
	v_lshlrev_b32_e32 v17, 16, v177
	v_lshlrev_b32_e32 v16, 16, v176
	v_and_b32_e32 v177, 0xffff0000, v177
	v_and_b32_e32 v176, 0xffff0000, v176
	v_pk_add_f32 v[18:19], v[16:17], v[176:177]
	v_pk_mul_f32 v[176:177], v[176:177], v[176:177]
	v_pk_add_f32 v[20:21], v[4:5], v[18:19]
	v_pk_fma_f32 v[176:177], v[16:17], v[16:17], v[176:177]
	s_nop 0
	v_add_f32_e32 v0, v5, v176
	v_pk_add_f32 v[4:5], v[176:177], v[0:1] op_sel_hi:[1,0]
	v_and_b32_e32 v176, 0xffff0000, v178
	v_lshlrev_b32_e32 v178, 16, v178
	v_and_b32_e32 v4, 0xffff0000, v179
	v_lshlrev_b32_e32 v179, 16, v179
	v_mov_b32_e32 v16, v178
	v_mov_b32_e32 v17, v176
	v_mul_f32_e32 v0, v178, v178
	v_mov_b32_e32 v177, v179
	v_pk_fma_f32 v[16:17], v[16:17], v[16:17], v[0:1] op_sel_hi:[1,1,0]
	v_pk_add_f32 v[176:177], v[178:179], v[176:177]
	v_mov_b32_e32 v16, v179
	v_pk_mul_f32 v[178:179], v[178:179], v[178:179]
	v_mul_f32_e32 v9, v4, v4
	v_mov_b32_e32 v177, v179
	v_pk_add_f32 v[178:179], v[18:19], v[20:21] op_sel:[1,0] op_sel_hi:[0,1]
	v_mov_b32_e32 v179, v9
	v_pk_add_f32 v[4:5], v[16:17], v[4:5]
	v_pk_add_f32 v[176:177], v[176:177], v[178:179]
	s_nop 0
	v_pk_add_f32 v[4:5], v[176:177], v[4:5]
	s_waitcnt vmcnt(6)
	v_lshlrev_b32_e32 v17, 16, v181
	v_lshlrev_b32_e32 v16, 16, v180
	v_and_b32_e32 v181, 0xffff0000, v181
	v_and_b32_e32 v180, 0xffff0000, v180
	v_pk_add_f32 v[18:19], v[16:17], v[180:181]
	v_pk_mul_f32 v[180:181], v[180:181], v[180:181]
	v_pk_add_f32 v[20:21], v[4:5], v[18:19]
	v_pk_fma_f32 v[180:181], v[16:17], v[16:17], v[180:181]
	s_nop 0
	v_add_f32_e32 v0, v5, v180
	v_pk_add_f32 v[4:5], v[180:181], v[0:1] op_sel_hi:[1,0]
	v_and_b32_e32 v180, 0xffff0000, v182
	v_lshlrev_b32_e32 v182, 16, v182
	v_and_b32_e32 v4, 0xffff0000, v183
	v_lshlrev_b32_e32 v183, 16, v183
	v_mov_b32_e32 v16, v182
	v_mov_b32_e32 v17, v180
	v_mul_f32_e32 v0, v182, v182
	v_mov_b32_e32 v181, v183
	v_pk_fma_f32 v[16:17], v[16:17], v[16:17], v[0:1] op_sel_hi:[1,1,0]
	v_pk_add_f32 v[180:181], v[182:183], v[180:181]
	v_mov_b32_e32 v16, v183
	v_pk_mul_f32 v[182:183], v[182:183], v[182:183]
	v_mul_f32_e32 v9, v4, v4
	v_mov_b32_e32 v181, v183
	v_pk_add_f32 v[182:183], v[18:19], v[20:21] op_sel:[1,0] op_sel_hi:[0,1]
	v_mov_b32_e32 v183, v9
	v_pk_add_f32 v[4:5], v[16:17], v[4:5]
	v_pk_add_f32 v[180:181], v[180:181], v[182:183]
	s_nop 0
	v_pk_add_f32 v[4:5], v[180:181], v[4:5]
	s_waitcnt vmcnt(5)
	v_lshlrev_b32_e32 v17, 16, v185
	v_lshlrev_b32_e32 v16, 16, v184
	v_and_b32_e32 v185, 0xffff0000, v185
	v_and_b32_e32 v184, 0xffff0000, v184
	v_pk_add_f32 v[18:19], v[16:17], v[184:185]
	v_pk_mul_f32 v[184:185], v[184:185], v[184:185]
	v_pk_add_f32 v[20:21], v[4:5], v[18:19]
	v_pk_fma_f32 v[184:185], v[16:17], v[16:17], v[184:185]
	s_nop 0
	v_add_f32_e32 v0, v5, v184
	v_pk_add_f32 v[4:5], v[184:185], v[0:1] op_sel_hi:[1,0]
	v_and_b32_e32 v184, 0xffff0000, v186
	v_lshlrev_b32_e32 v186, 16, v186
	v_and_b32_e32 v4, 0xffff0000, v187
	v_lshlrev_b32_e32 v187, 16, v187
	v_mov_b32_e32 v16, v186
	v_mov_b32_e32 v17, v184
	v_mul_f32_e32 v0, v186, v186
	v_mov_b32_e32 v185, v187
	v_pk_fma_f32 v[16:17], v[16:17], v[16:17], v[0:1] op_sel_hi:[1,1,0]
	v_pk_add_f32 v[184:185], v[186:187], v[184:185]
	v_mov_b32_e32 v16, v187
	v_pk_mul_f32 v[186:187], v[186:187], v[186:187]
	v_mul_f32_e32 v9, v4, v4
	v_mov_b32_e32 v185, v187
	v_pk_add_f32 v[186:187], v[18:19], v[20:21] op_sel:[1,0] op_sel_hi:[0,1]
	v_mov_b32_e32 v187, v9
	v_pk_add_f32 v[4:5], v[16:17], v[4:5]
	v_pk_add_f32 v[184:185], v[184:185], v[186:187]
	s_nop 0
	v_pk_add_f32 v[4:5], v[184:185], v[4:5]
	s_waitcnt vmcnt(4)
	v_lshlrev_b32_e32 v17, 16, v189
	v_lshlrev_b32_e32 v16, 16, v188
	v_and_b32_e32 v189, 0xffff0000, v189
	v_and_b32_e32 v188, 0xffff0000, v188
	v_pk_add_f32 v[18:19], v[16:17], v[188:189]
	v_pk_mul_f32 v[188:189], v[188:189], v[188:189]
	v_pk_add_f32 v[20:21], v[4:5], v[18:19]
	v_pk_fma_f32 v[188:189], v[16:17], v[16:17], v[188:189]
	s_nop 0
	v_add_f32_e32 v0, v5, v188
	v_pk_add_f32 v[4:5], v[188:189], v[0:1] op_sel_hi:[1,0]
	v_and_b32_e32 v188, 0xffff0000, v190
	v_lshlrev_b32_e32 v190, 16, v190
	v_and_b32_e32 v4, 0xffff0000, v191
	v_lshlrev_b32_e32 v191, 16, v191
	v_mov_b32_e32 v16, v190
	v_mov_b32_e32 v17, v188
	v_mul_f32_e32 v0, v190, v190
	v_mov_b32_e32 v189, v191
	v_pk_fma_f32 v[16:17], v[16:17], v[16:17], v[0:1] op_sel_hi:[1,1,0]
	v_pk_add_f32 v[188:189], v[190:191], v[188:189]
	v_mov_b32_e32 v16, v191
	v_pk_mul_f32 v[190:191], v[190:191], v[190:191]
	v_mul_f32_e32 v9, v4, v4
	v_mov_b32_e32 v189, v191
	v_pk_add_f32 v[190:191], v[18:19], v[20:21] op_sel:[1,0] op_sel_hi:[0,1]
	v_mov_b32_e32 v191, v9
	v_pk_add_f32 v[4:5], v[16:17], v[4:5]
	v_pk_add_f32 v[188:189], v[188:189], v[190:191]
	s_nop 0
	v_pk_add_f32 v[4:5], v[188:189], v[4:5]
	s_waitcnt vmcnt(3)
; __device__ __forceinline__ float bf_lo(unsigned w) { return __uint_as_float(w << 16); }
; __device__ __forceinline__ float bf_hi(unsigned w) { return __uint_as_float(w & 0xffff0000u); }
; __device__ __forceinline__ float shx(float v, int o, int lane) { return __int_as_float(__builtin_amdgcn_ds_bpermute((lane ^ o) << 2, __float_as_int(v))); }
; __device__ __forceinline__ void gate_unit(LAS unsigned char* lds, bf16_t* Zg, int ch, const bf16_t* wsb, const float* ln_g, const float* ln_b, const float* b_s, bool dostore = true) {
;     ...
;         for (int i = 0; i < 32; ++i) { const u32x4 w = *(const u32x4*)(src + i * 32);
; #pragma unroll
;             for (int e = 0; e < 4; ++e) { const float a = bf_lo(w[e]), b = bf_hi(w[e]); s += a + b; s2 += a * a + b * b; } }
;         s += shx(s, 1, lane); s += shx(s, 2, lane); s2 += shx(s2, 1, lane); s2 += shx(s2, 2, lane);
;         const float mean = s * (1.0f / 1024.0f); const float var = fmaxf(s2 * (1.0f / 1024.0f) - mean * mean, 0.f);
;         if (part == 0) { stats[row * 2] = mean; stats[row * 2 + 1] = 1.0f / sqrtf(var + EPS); }
	v_lshlrev_b32_e32 v17, 16, v81
	v_lshlrev_b32_e32 v16, 16, v80
	v_and_b32_e32 v81, 0xffff0000, v81
	v_and_b32_e32 v80, 0xffff0000, v80
	v_pk_add_f32 v[18:19], v[16:17], v[80:81]
	v_pk_mul_f32 v[80:81], v[80:81], v[80:81]
	v_pk_add_f32 v[20:21], v[4:5], v[18:19]
	v_pk_fma_f32 v[80:81], v[16:17], v[16:17], v[80:81]
	s_nop 0
	v_add_f32_e32 v0, v5, v80
	v_pk_add_f32 v[4:5], v[80:81], v[0:1] op_sel_hi:[1,0]
	v_and_b32_e32 v80, 0xffff0000, v82
	v_lshlrev_b32_e32 v82, 16, v82
	v_and_b32_e32 v4, 0xffff0000, v83
	v_lshlrev_b32_e32 v83, 16, v83
	v_mov_b32_e32 v16, v82
	v_mov_b32_e32 v17, v80
	v_mul_f32_e32 v0, v82, v82
	v_mov_b32_e32 v81, v83
	v_pk_fma_f32 v[16:17], v[16:17], v[16:17], v[0:1] op_sel_hi:[1,1,0]
	v_pk_add_f32 v[80:81], v[82:83], v[80:81]
	v_mov_b32_e32 v16, v83
	v_pk_mul_f32 v[82:83], v[82:83], v[82:83]
	v_mul_f32_e32 v9, v4, v4
	v_mov_b32_e32 v81, v83
	v_pk_add_f32 v[82:83], v[18:19], v[20:21] op_sel:[1,0] op_sel_hi:[0,1]
	v_mov_b32_e32 v83, v9
	v_pk_add_f32 v[4:5], v[16:17], v[4:5]
	v_pk_add_f32 v[80:81], v[80:81], v[82:83]
	s_nop 0
	v_pk_add_f32 v[4:5], v[80:81], v[4:5]
	s_waitcnt vmcnt(2)
	v_lshlrev_b32_e32 v17, 16, v85
	v_lshlrev_b32_e32 v16, 16, v84
	v_and_b32_e32 v85, 0xffff0000, v85
	v_and_b32_e32 v84, 0xffff0000, v84
	v_pk_add_f32 v[18:19], v[16:17], v[84:85]
	v_pk_mul_f32 v[84:85], v[84:85], v[84:85]
	v_pk_add_f32 v[20:21], v[4:5], v[18:19]
	v_pk_fma_f32 v[84:85], v[16:17], v[16:17], v[84:85]
	s_nop 0
	v_add_f32_e32 v0, v5, v84
	v_pk_add_f32 v[4:5], v[84:85], v[0:1] op_sel_hi:[1,0]
	v_and_b32_e32 v84, 0xffff0000, v86
	v_lshlrev_b32_e32 v86, 16, v86
	v_and_b32_e32 v4, 0xffff0000, v87
	v_lshlrev_b32_e32 v87, 16, v87
	v_mov_b32_e32 v16, v86
	v_mov_b32_e32 v17, v84
	v_mul_f32_e32 v0, v86, v86
	v_mov_b32_e32 v85, v87
	v_pk_fma_f32 v[16:17], v[16:17], v[16:17], v[0:1] op_sel_hi:[1,1,0]
	v_pk_add_f32 v[84:85], v[86:87], v[84:85]
	v_mov_b32_e32 v16, v87
	v_pk_mul_f32 v[86:87], v[86:87], v[86:87]
	v_mul_f32_e32 v9, v4, v4
	v_mov_b32_e32 v85, v87
	v_pk_add_f32 v[86:87], v[18:19], v[20:21] op_sel:[1,0] op_sel_hi:[0,1]
	v_mov_b32_e32 v87, v9
	v_pk_add_f32 v[4:5], v[16:17], v[4:5]
	v_pk_add_f32 v[84:85], v[84:85], v[86:87]
	s_nop 0
	v_pk_add_f32 v[4:5], v[84:85], v[4:5]
	s_waitcnt vmcnt(1)
	v_lshlrev_b32_e32 v17, 16, v89
	v_lshlrev_b32_e32 v16, 16, v88
	v_and_b32_e32 v89, 0xffff0000, v89
	v_and_b32_e32 v88, 0xffff0000, v88
	v_pk_add_f32 v[18:19], v[16:17], v[88:89]
	v_pk_mul_f32 v[88:89], v[88:89], v[88:89]
	v_pk_add_f32 v[20:21], v[4:5], v[18:19]
	v_pk_fma_f32 v[88:89], v[16:17], v[16:17], v[88:89]
	s_nop 0
	v_add_f32_e32 v0, v5, v88
	v_pk_add_f32 v[4:5], v[88:89], v[0:1] op_sel_hi:[1,0]
	v_and_b32_e32 v88, 0xffff0000, v90
	v_lshlrev_b32_e32 v90, 16, v90
	v_and_b32_e32 v4, 0xffff0000, v91
	v_lshlrev_b32_e32 v91, 16, v91
	v_mov_b32_e32 v16, v90
	v_mov_b32_e32 v17, v88
	v_mul_f32_e32 v0, v90, v90
	v_mov_b32_e32 v89, v91
	v_pk_fma_f32 v[16:17], v[16:17], v[16:17], v[0:1] op_sel_hi:[1,1,0]
	v_pk_add_f32 v[88:89], v[90:91], v[88:89]
	v_mov_b32_e32 v16, v91
	v_pk_mul_f32 v[90:91], v[90:91], v[90:91]
	v_mul_f32_e32 v9, v4, v4
	v_mov_b32_e32 v89, v91
	v_pk_add_f32 v[90:91], v[18:19], v[20:21] op_sel:[1,0] op_sel_hi:[0,1]
	v_mov_b32_e32 v91, v9
	v_pk_add_f32 v[4:5], v[16:17], v[4:5]
	v_pk_add_f32 v[88:89], v[88:89], v[90:91]
	s_nop 0
	v_pk_add_f32 v[4:5], v[88:89], v[4:5]
	s_waitcnt vmcnt(0)
	v_lshlrev_b32_e32 v15, 16, v93
	v_lshlrev_b32_e32 v14, 16, v92
	v_and_b32_e32 v93, 0xffff0000, v93
	v_and_b32_e32 v92, 0xffff0000, v92
	v_pk_add_f32 v[16:17], v[14:15], v[92:93]
	v_pk_mul_f32 v[92:93], v[92:93], v[92:93]
	v_pk_add_f32 v[18:19], v[4:5], v[16:17]
	v_pk_fma_f32 v[92:93], v[14:15], v[14:15], v[92:93]
	s_nop 0
	v_add_f32_e32 v0, v5, v92
	v_pk_add_f32 v[4:5], v[92:93], v[0:1] op_sel_hi:[1,0]
	v_and_b32_e32 v92, 0xffff0000, v94
	v_lshlrev_b32_e32 v94, 16, v94
	v_and_b32_e32 v4, 0xffff0000, v95
	v_lshlrev_b32_e32 v95, 16, v95
	v_mov_b32_e32 v14, v94
	v_mov_b32_e32 v15, v92
	v_mul_f32_e32 v0, v94, v94
	v_mov_b32_e32 v93, v95
	v_pk_fma_f32 v[14:15], v[14:15], v[14:15], v[0:1] op_sel_hi:[1,1,0]
	v_pk_add_f32 v[92:93], v[94:95], v[92:93]
	v_mov_b32_e32 v14, v95
	v_pk_mul_f32 v[94:95], v[94:95], v[94:95]
	v_mul_f32_e32 v9, v4, v4
	v_mov_b32_e32 v93, v95
	v_pk_add_f32 v[94:95], v[16:17], v[18:19] op_sel:[1,0] op_sel_hi:[0,1]
	v_mov_b32_e32 v95, v9
	v_pk_add_f32 v[4:5], v[14:15], v[4:5]
	v_pk_add_f32 v[92:93], v[92:93], v[94:95]
	s_nop 0
	v_pk_add_f32 v[4:5], v[92:93], v[4:5]
	s_cbranch_scc0 .LBB0_179
	v_and_b32_e32 v0, 63, v6
	v_lshlrev_b32_e32 v2, 2, v0
	v_xor_b32_e32 v3, 4, v2
	ds_bpermute_b32 v9, v3, v4
	ds_bpermute_b32 v3, v3, v5
	v_xor_b32_e32 v10, 8, v2
	v_readfirstlane_b32 s10, v6
	v_cmp_eq_u32_e32 vcc, 0, v8
	s_waitcnt lgkmcnt(1)
	v_add_f32_e32 v2, v4, v9
	s_waitcnt lgkmcnt(0)
	v_add_f32_e32 v4, v5, v3
	ds_bpermute_b32 v3, v10, v2
	ds_bpermute_b32 v5, v10, v4
	s_and_saveexec_b64 s[74:75], vcc
	s_cbranch_execz .LBB0_182
	s_waitcnt lgkmcnt(1)
	v_add_f32_e32 v2, v2, v3
	v_mul_f32_e32 v2, 0x3a800000, v2
	s_waitcnt lgkmcnt(0)
	v_add_f32_e32 v4, v4, v5
	v_mul_f32_e32 v3, v2, v2
	s_mov_b32 s4, 0x3a800000
	v_fma_f32 v3, v4, s4, -v3
	v_max_f32_e32 v3, 0, v3
	v_add_f32_e32 v3, 0x358637bd, v3
	v_mul_f32_e32 v4, 0x4f800000, v3
	v_cmp_gt_f32_e32 vcc, s36, v3
	v_lshl_add_u32 v7, v7, 3, 0
	s_nop 0
	v_cndmask_b32_e32 v3, v3, v4, vcc
	v_sqrt_f32_e32 v4, v3
	s_nop 0
	v_add_u32_e32 v5, -1, v4
	v_fma_f32 v8, -v5, v4, v3
	v_cmp_ge_f32_e64 s[4:5], 0, v8
	v_add_u32_e32 v8, 1, v4
	s_nop 0
	v_cndmask_b32_e64 v5, v4, v5, s[4:5]
	v_fma_f32 v4, -v8, v4, v3
	v_cmp_lt_f32_e64 s[4:5], 0, v4
	s_nop 1
	v_cndmask_b32_e64 v4, v5, v8, s[4:5]
	v_mul_f32_e32 v5, 0x37800000, v4
	v_cndmask_b32_e32 v4, v4, v5, vcc
	v_cmp_class_f32_e32 vcc, v3, v205
	s_nop 1
	v_cndmask_b32_e32 v3, v4, v3, vcc
	v_div_scale_f32 v4, s[4:5], v3, v3, 1.0
	v_rcp_f32_e32 v5, v4
	s_nop 0
	v_fma_f32 v8, -v4, v5, 1.0
	v_fmac_f32_e32 v5, v8, v5
	v_div_scale_f32 v8, vcc, 1.0, v3, 1.0
	v_mul_f32_e32 v9, v8, v5
	v_fma_f32 v10, -v4, v9, v8
	v_fmac_f32_e32 v9, v10, v5
	v_fma_f32 v4, -v4, v9, v8
	v_div_fmas_f32 v4, v4, v5, v9
	v_div_fixup_f32 v3, v4, v3, 1.0
	ds_write_b64 v7, v[2:3]
